# mixers tail (sample-row items): work-queue grab issued one round ahead (atomic round trip hidden behind the current items)
# speedup vs baseline: 1.0682x; 1.0028x over previous
; __device__ __forceinline__ int hw_lane() { int ln; asm volatile("v_mbcnt_lo_u32_b32 %0, -1, 0\n\tv_mbcnt_hi_u32_b32 %0, -1, %0" : "=v"(ln)); return ln; }
;     ...
;         constexpr int N_GS = DB * 8, N_NS = DB * 2 * 25, N_ALL = N_GS + N_NS;
;         for (;;) {
;             if (c.wave == 0 && hw_lane() == 0) { unsigned* head = c.ctl + (l ? CW_Q1 : CW_Q0) + rep * 1024; *slot = __hip_atomic_fetch_add(head, 8u, __ATOMIC_RELAXED, __HIP_MEMORY_SCOPE_AGENT); }
;             __syncthreads();
;             const unsigned base = *slot;
;             __syncthreads();
.LBB0_1358:
	s_nop 0
	v_readlane_b32 s0, v254, 54
	v_readlane_b32 s1, v254, 55
	s_andn2_b64 vcc, exec, s[0:1]
	s_movk_i32 s33, 0x4000
	s_cbranch_vccnz .LBB0_1175
	v_readlane_b32 s0, v254, 46
	v_mbcnt_lo_u32_b32 v0, -1, 0
	v_mbcnt_hi_u32_b32 v0, -1, v0
	v_readlane_b32 s1, v253, 17
	s_lshl_b32 s1, s0, 12
	s_add_i32 s1, s1, 0
	s_cmp_eq_u32 s0, 0
	v_readlane_b32 s2, v254, 53
	v_readlane_b32 s6, v255, 18
	s_cselect_b64 s[4:5], -1, 0
	v_readlane_b32 s7, v255, 19
	s_add_u32 s6, s2, s6
	v_readlane_b32 s2, v255, 2
	s_addc_u32 s7, s2, s7
	s_andn2_b64 vcc, exec, s[4:5]
	s_cbranch_vccnz .Lpc_skipA
	v_mbcnt_lo_u32_b32 v0, -1, 0
	v_mbcnt_hi_u32_b32 v0, -1, v0
	v_cmp_eq_u32_e32 vcc, 0, v0
	s_and_saveexec_b64 s[2:3], vcc
	v_mov_b32_e32 v201, 8
	global_atomic_add v200, v1, v201, s[6:7] sc0
	s_or_b64 exec, exec, s[2:3]
.Lpc_skipA:
	s_branch .LBB0_1363
.LBB0_1360:
	s_or_b64 exec, exec, s[8:9]
	v_lshl_add_u64 v[2:3], v[58:59], 2, s[2:3]
	global_store_dword v[2:3], v22, off offset:32
	global_store_dword v[2:3], v21, off offset:288
	global_store_dword v[2:3], v20, off offset:544
	global_store_dword v[2:3], v14, off offset:800

; #define LAS __attribute__((address_space(3)))
; __device__ __forceinline__ int hw_lane() { int ln; asm volatile("v_mbcnt_lo_u32_b32 %0, -1, 0\n\tv_mbcnt_hi_u32_b32 %0, -1, %0" : "=v"(ln)); return ln; }
; #define AIN(i) ld_ptr(c.la + 2 * (i))
; __device__ __forceinline__ void gdn_item_sample(const Ctx& c, int l, int b, int hh, LAS float* wl, int lane) {
;     const float* s0 = (const float*)AIN(I_SGDN) + (((size_t)l * DB + b) * 8 + hh) * 4096;
;     float S[64];
; #pragma unroll
;     for (int d = 0; d < 64; ++d) S[d] = __builtin_nontemporal_load(s0 + d * 64 + lane);
;     gdn_steps(c, l, MPR + b, 1, hh, S, wl, lane);
;     ...
;             if (c.wave == 0 && hw_lane() == 0) { unsigned* head = c.ctl + (l ? CW_Q1 : CW_Q0) + rep * 1024; *slot = __hip_atomic_fetch_add(head, 8u, __ATOMIC_RELAXED, __HIP_MEMORY_SCOPE_AGENT); }
;             __syncthreads();
;             const unsigned base = *slot;
;             __syncthreads();
;             if (base >= (unsigned)N_ALL) break;
; #pragma unroll 1
;             for (int k = 0; k < 1; ++k) { const unsigned it = base + (unsigned)(k * 8 + c.wave);
;                 if (it < (unsigned)N_ALL) { int ln = hw_lane(); asm volatile("" : "+v"(ln));
;                     if (it < (unsigned)N_NS) sample_part(c, l, (int)it, wl, ln);
;                     else { const int kk = (int)it - N_NS; gdn_item_sample(c, l, kk >> 3, kk & 7, wl, ln); } } }
.LBB0_1363:
	s_andn2_b64 vcc, exec, s[4:5]
	s_cbranch_vccnz .LBB0_1369
	v_mbcnt_lo_u32_b32 v0, -1, 0
	v_mbcnt_hi_u32_b32 v0, -1, v0
	v_cmp_eq_u32_e32 vcc, 0, v0
	s_and_saveexec_b64 s[2:3], vcc
	s_waitcnt vmcnt(0)
	ds_write_b32 v1, v200 offset:64
	s_or_b64 exec, exec, s[2:3]
.LBB0_1369:
	s_waitcnt lgkmcnt(0)
	s_barrier
	ds_read_b32 v0, v1 offset:64
	s_movk_i32 s2, 0x1cff
	s_waitcnt lgkmcnt(0)
	s_barrier
	v_cmp_lt_u32_e32 vcc, s2, v0
	v_readfirstlane_b32 s12, v0
	s_mov_b64 s[2:3], -1
	s_cbranch_vccnz .LBB0_1362
	s_andn2_b64 vcc, exec, s[4:5]
	s_cbranch_vccnz .Lpc_skipB
	v_mbcnt_lo_u32_b32 v0, -1, 0
	v_mbcnt_hi_u32_b32 v0, -1, v0
	v_cmp_eq_u32_e32 vcc, 0, v0
	s_and_saveexec_b64 s[2:3], vcc
	v_mov_b32_e32 v201, 8
	global_atomic_add v200, v1, v201, s[6:7] sc0
	s_or_b64 exec, exec, s[2:3]
.Lpc_skipB:
	s_add_i32 s12, s12, s0
	s_cmpk_gt_u32 s12, 0x1cff
	s_cbranch_scc1 .LBB0_1361
	v_mbcnt_lo_u32_b32 v58, -1, 0
	v_mbcnt_hi_u32_b32 v58, -1, v58
	s_cmpk_gt_u32 s12, 0x18ff
	s_nop 0
	v_ashrrev_i32_e32 v59, 31, v58
	s_cbranch_scc0 .LBB0_1373
	s_add_i32 s2, s12, 0xffffe700
	ds_read_b32 v0, v1 offset:288
	ds_read_b32 v2, v1 offset:292
	s_lshr_b32 s3, s2, 3
	s_lshl_b32 s2, s2, 12
	v_readlane_b32 s8, v255, 22
	s_and_b32 s13, s12, 7
	s_or_b32 s30, s2, s8
	s_or_b32 s2, s3, 0x4000
	s_mov_b32 s3, s31
	s_lshl_b64 s[16:17], s[2:3], 9
	s_lshl_b32 s8, s13, 6
	s_or_b32 s16, s16, s8
	s_lshl_b64 s[8:9], s[2:3], 7
	s_waitcnt lgkmcnt(1)
	v_readfirstlane_b32 s3, v0
	s_lshl_b64 s[10:11], s[30:31], 2
	s_waitcnt lgkmcnt(0)
	v_readfirstlane_b32 s19, v2
	s_add_u32 s18, s3, s10
	s_addc_u32 s19, s19, s11
	v_lshlrev_b64 v[54:55], 2, v[58:59]
	v_lshl_add_u64 v[2:3], s[18:19], 0, v[54:55]
	s_movk_i32 s3, 0x1000
	v_add_co_u32_e32 v4, vcc, s3, v2
	s_movk_i32 s3, 0x2000
	s_nop 0
	v_addc_co_u32_e32 v5, vcc, 0, v3, vcc
	v_add_co_u32_e32 v6, vcc, s3, v2
	s_movk_i32 s3, 0x3000
	s_nop 0
	v_addc_co_u32_e32 v7, vcc, 0, v3, vcc
	global_load_dword v122, v[2:3], off nt
	global_load_dword v104, v[2:3], off offset:256 nt
	global_load_dword v123, v[2:3], off offset:512 nt
	global_load_dword v105, v[2:3], off offset:768 nt
	global_load_dword v120, v[2:3], off offset:1024 nt
	global_load_dword v102, v[2:3], off offset:1280 nt
	global_load_dword v121, v[2:3], off offset:1536 nt
	global_load_dword v103, v[2:3], off offset:1792 nt
	global_load_dword v118, v[2:3], off offset:2048 nt
	global_load_dword v100, v[2:3], off offset:2304 nt
	global_load_dword v119, v[2:3], off offset:2560 nt
	global_load_dword v101, v[2:3], off offset:2816 nt
	global_load_dword v116, v[2:3], off offset:3072 nt
	global_load_dword v98, v[2:3], off offset:3328 nt
	global_load_dword v117, v[2:3], off offset:3584 nt
	global_load_dword v99, v[2:3], off offset:3840 nt
	v_add_co_u32_e32 v2, vcc, s3, v2
	global_load_dword v112, v[4:5], off offset:256 nt
	global_load_dword v125, v[4:5], off offset:512 nt
	global_load_dword v113, v[4:5], off offset:768 nt
	global_load_dword v110, v[4:5], off offset:1024 nt
	global_load_dword v108, v[4:5], off offset:1280 nt
	global_load_dword v111, v[4:5], off offset:1536 nt
	global_load_dword v109, v[4:5], off offset:1792 nt
	global_load_dword v106, v[4:5], off offset:2048 nt
	global_load_dword v88, v[6:7], off nt
	global_load_dword v86, v[6:7], off offset:256 nt
	global_load_dword v89, v[6:7], off offset:512 nt
	global_load_dword v87, v[6:7], off offset:768 nt
	global_load_dword v84, v[6:7], off offset:1024 nt
	global_load_dword v82, v[6:7], off offset:1280 nt
	global_load_dword v85, v[6:7], off offset:1536 nt
	global_load_dword v83, v[6:7], off offset:1792 nt
	global_load_dword v80, v[6:7], off offset:2048 nt
	global_load_dword v78, v[6:7], off offset:2304 nt
	global_load_dword v81, v[6:7], off offset:2560 nt
	global_load_dword v79, v[6:7], off offset:2816 nt
	global_load_dword v72, v[6:7], off offset:3072 nt
	global_load_dword v70, v[6:7], off offset:3328 nt
	global_load_dword v73, v[6:7], off offset:3584 nt
	global_load_dword v71, v[6:7], off offset:3840 nt
	v_addc_co_u32_e32 v3, vcc, 0, v3, vcc
	global_load_dword v114, v[4:5], off offset:2304 nt
	global_load_dword v107, v[4:5], off offset:2560 nt
	global_load_dword v115, v[4:5], off offset:2816 nt
	global_load_dword v94, v[4:5], off offset:3072 nt
	global_load_dword v92, v[4:5], off offset:3328 nt
	global_load_dword v95, v[4:5], off offset:3584 nt
	global_load_dword v93, v[4:5], off offset:3840 nt
	global_load_dword v76, v[2:3], off nt
	global_load_dword v74, v[2:3], off offset:256 nt
	global_load_dword v77, v[2:3], off offset:512 nt
	global_load_dword v75, v[2:3], off offset:768 nt
	global_load_dword v68, v[2:3], off offset:1024 nt
	global_load_dword v66, v[2:3], off offset:1280 nt
	global_load_dword v69, v[2:3], off offset:1536 nt
	global_load_dword v67, v[2:3], off offset:1792 nt
	global_load_dword v64, v[2:3], off offset:2048 nt
	global_load_dword v124, v[6:7], off offset:-4096 nt
	global_load_dword v62, v[2:3], off offset:2304 nt
	global_load_dword v65, v[2:3], off offset:2560 nt
	global_load_dword v63, v[2:3], off offset:2816 nt
	global_load_dword v60, v[2:3], off offset:3072 nt
	global_load_dword v56, v[2:3], off offset:3328 nt
	global_load_dword v61, v[2:3], off offset:3584 nt
	global_load_dword v57, v[2:3], off offset:3840 nt
	ds_read_b32 v0, v1 offset:464
	ds_read_b32 v2, v1 offset:468
	ds_read_b32 v3, v1 offset:464
	ds_read_b32 v4, v1 offset:468
	s_mov_b32 s3, 0x35600000
	s_waitcnt lgkmcnt(3)
	v_readfirstlane_b32 s18, v0
	s_waitcnt lgkmcnt(2)
	v_readfirstlane_b32 s19, v2
	s_waitcnt lgkmcnt(1)
	v_readfirstlane_b32 s22, v3
	v_lshl_add_u64 v[2:3], s[16:17], 0, v[58:59]
	s_waitcnt lgkmcnt(0)
; #define LAS __attribute__((address_space(3)))
; __device__ __forceinline__ float bf2f(bf16 v) { return __uint_as_float(((unsigned)v) << 16); }
; __device__ __forceinline__ void wave_lds_sync() { asm volatile("s_waitcnt lgkmcnt(0)" ::: "memory"); }
; #define AIN(i) ld_ptr(c.la + 2 * (i))
; __device__ __forceinline__ void gdn_steps(const Ctx& c, int l, int row0, int nsteps, int hh, float (&S)[64], LAS float* wl, int lane) {
;     const float* GQ = (const float*)(AWS + WS_GQ); const float* GK = (const float*)(AWS + WS_GK); const float* GV = (const float*)(AWS + WS_GV);
;     const float* SC = (const float*)(AWS + WS_SC);
;     const bf16* H = (const bf16*)(AWS + WS_H); bf16* MIX = (bf16*)(AWS + WS_MIX);
;     const float nw = ((const float*)AIN(I_GNW))[l * 64 + lane];
;     LAS float* kb = wl; LAS float* qb = wl + 64;
;     size_t o = (size_t)row0 * 512 + hh * 64 + lane;
;     float nk = GK[o], nq = GQ[o], nv = GV[o], ng = SC[((size_t)row0 * 8 + hh) * 4], nb = SC[((size_t)row0 * 8 + hh) * 4 + 1], nz = bf2f(H[(size_t)row0 * HW + HGZ + hh * 64 + lane]);
;     for (int s = 0; s < nsteps; ++s) {
;         const int m = row0 + s;
;         const float kv = nk, qv = nq, vv = nv, gv = ng, bv = nb, zv = nz;
;         if (s + 1 < nsteps) { const size_t o2 = (size_t)(m + 1) * 512 + hh * 64 + lane;
;             nk = GK[o2]; nq = GQ[o2]; nv = GV[o2]; ng = SC[((size_t)(m + 1) * 8 + hh) * 4]; nb = SC[((size_t)(m + 1) * 8 + hh) * 4 + 1]; nz = bf2f(H[(size_t)(m + 1) * HW + HGZ + hh * 64 + lane]); }
;         wave_lds_sync(); kb[lane] = kv; qb[lane] = qv; wave_lds_sync();
;         const float al = gv;
;         float u0 = 0.f, u1 = 0.f, u2 = 0.f, u3 = 0.f;
; #pragma unroll
;         for (int d = 0; d < 64; d += 4) { const f32x4 k4 = *(const LAS f32x4*)(kb + d); u0 += k4[0] * S[d]; u1 += k4[1] * S[d + 1]; u2 += k4[2] * S[d + 2]; u3 += k4[3] * S[d + 3]; }
	v_readfirstlane_b32 s23, v4
	v_lshlrev_b64 v[2:3], 2, v[2:3]
	ds_read_b32 v0, v1 offset:464
	ds_read_b32 v6, v1 offset:468
	ds_read_b32 v7, v1 offset:464
	ds_read_b32 v8, v1 offset:468
	ds_read_b32 v9, v1 offset:464
	ds_read_b32 v10, v1 offset:468
	ds_read_b32 v138, v1 offset:464
	ds_read_b32 v139, v1 offset:468
	ds_read_b32 v11, v1 offset:384
	ds_read_b32 v12, v1 offset:388
	v_lshl_add_u64 v[4:5], s[22:23], 0, v[2:3]
	v_add_co_u32_e32 v4, vcc, s3, v4
	s_mov_b32 s3, 0x33500000
	s_nop 0
	v_addc_co_u32_e32 v5, vcc, 0, v5, vcc
	global_load_dword v13, v[4:5], off
	v_lshl_add_u64 v[4:5], s[18:19], 0, v[2:3]
	v_add_co_u32_e32 v4, vcc, s3, v4
	s_waitcnt lgkmcnt(9)
	v_readfirstlane_b32 s16, v0
	v_addc_co_u32_e32 v5, vcc, 0, v5, vcc
	global_load_dword v14, v[4:5], off
	s_waitcnt lgkmcnt(8)
	v_readfirstlane_b32 s17, v6
	s_waitcnt lgkmcnt(7)
	v_readfirstlane_b32 s19, v7
	s_waitcnt lgkmcnt(6)
	v_readfirstlane_b32 s20, v8
	v_lshl_add_u64 v[2:3], s[16:17], 0, v[2:3]
	s_mov_b32 s16, 0x37700000
	s_add_u32 s8, s19, s8
	v_add_co_u32_e32 v2, vcc, s16, v2
	s_addc_u32 s9, s20, s9
	s_lshl_b32 s16, s13, 4
	v_addc_co_u32_e32 v3, vcc, 0, v3, vcc
	s_add_u32 s8, s8, s16
	global_load_dword v141, v[2:3], off
	s_addc_u32 s9, s9, 0
	v_mov_b32_e32 v2, 0x3a600000
	global_load_dwordx2 v[96:97], v2, s[8:9]
	s_mul_i32 s18, s2, 0x1c00
	s_waitcnt lgkmcnt(5)
	v_readfirstlane_b32 s22, v9
	s_mul_hi_u32 s3, s2, 0x1c00
	s_waitcnt lgkmcnt(4)
	v_readfirstlane_b32 s23, v10
	s_add_u32 s8, s22, s18
	s_waitcnt lgkmcnt(1)
	v_readfirstlane_b32 s24, v11
	s_addc_u32 s9, s23, s3
	s_lshl_b32 s3, s13, 7
	v_mov_b32_e32 v4, s24
	v_readlane_b32 s24, v255, 23
	s_add_u32 s8, s8, s3
	s_waitcnt lgkmcnt(0)
	v_readfirstlane_b32 s25, v12
	v_add_u32_e32 v6, s24, v58
	s_addc_u32 s9, s9, 0
	v_lshlrev_b64 v[90:91], 1, v[58:59]
	v_mov_b32_e32 v5, s25
	v_ashrrev_i32_e32 v7, 31, v6
	v_lshl_add_u64 v[2:3], s[8:9], 0, v[90:91]
	s_mov_b32 s8, 0xfd01000
	v_lshl_add_u64 v[4:5], v[6:7], 2, v[4:5]
	v_add_co_u32_e32 v2, vcc, s8, v2
	global_load_dword v0, v[4:5], off
	v_lshl_add_u32 v4, v58, 2, s1
	v_addc_co_u32_e32 v3, vcc, 0, v3, vcc
	global_load_ushort v140, v[2:3], off offset:1536
	s_waitcnt lgkmcnt(0)
	v_mov_b32_e32 v183, s1
	s_lshl_b32 s2, s2, 11
	v_readfirstlane_b32 s8, v138
	s_or_b32 s2, s2, s3
	v_readfirstlane_b32 s9, v139
	s_add_u32 s2, s8, s2
	s_addc_u32 s3, s9, 0
	s_waitcnt vmcnt(4)
	ds_write2st64_b32 v4, v13, v14 offset0:4 offset1:5
	s_waitcnt lgkmcnt(0)
	ds_read_b128 v[46:49], v183 offset:1024
	ds_read_b128 v[42:45], v183 offset:1040
	ds_read_b128 v[36:39], v183 offset:1056
	ds_read_b128 v[32:35], v183 offset:1072
	ds_read_b128 v[28:31], v183 offset:1088
	s_waitcnt lgkmcnt(4)
	v_mov_b32_e32 v170, v46
	v_mov_b32_e32 v171, v48
	v_pk_fma_f32 v[2:3], v[122:123], v[170:171], 0 op_sel_hi:[1,1,0]
	s_waitcnt lgkmcnt(3)
	v_mov_b32_e32 v172, v42
	v_mov_b32_e32 v173, v44
	v_pk_fma_f32 v[2:3], v[120:121], v[172:173], v[2:3]
	s_waitcnt lgkmcnt(2)
	v_mov_b32_e32 v174, v36
	v_mov_b32_e32 v175, v38
	v_pk_fma_f32 v[2:3], v[118:119], v[174:175], v[2:3]
	s_waitcnt lgkmcnt(1)
	v_mov_b32_e32 v176, v32
	v_mov_b32_e32 v177, v34
	v_pk_fma_f32 v[2:3], v[116:117], v[176:177], v[2:3]
	ds_read_b128 v[50:53], v183 offset:1104
	s_waitcnt lgkmcnt(1)
	v_mov_b32_e32 v178, v28
	v_mov_b32_e32 v179, v30
	v_mov_b32_e32 v48, v47
	v_pk_fma_f32 v[126:127], v[124:125], v[178:179], v[2:3]
	v_pk_fma_f32 v[2:3], v[104:105], v[48:49], 0 op_sel_hi:[1,1,0]
	v_mov_b32_e32 v44, v43
	v_pk_fma_f32 v[2:3], v[102:103], v[44:45], v[2:3]
	v_mov_b32_e32 v38, v37
	v_pk_fma_f32 v[2:3], v[100:101], v[38:39], v[2:3]
	v_mov_b32_e32 v34, v33
	v_pk_fma_f32 v[2:3], v[98:99], v[34:35], v[2:3]
	v_mov_b32_e32 v30, v29
	v_pk_fma_f32 v[32:33], v[112:113], v[30:31], v[2:3]
	s_waitcnt lgkmcnt(0)
	v_mov_b32_e32 v36, v50
	v_mov_b32_e32 v37, v52
	v_mov_b32_e32 v52, v51
	ds_read_b128 v[142:145], v183 offset:1120
	ds_read_b128 v[146:149], v183 offset:1136
	ds_read_b128 v[40:43], v183 offset:1152
	ds_read_b128 v[26:29], v183 offset:1168
	ds_read_b128 v[22:25], v183 offset:1184
	ds_read_b128 v[18:21], v183 offset:1200
	ds_read_b128 v[14:17], v183 offset:1216
	ds_read_b128 v[10:13], v183 offset:1232
	ds_read_b128 v[6:9], v183 offset:1248
	ds_read_b128 v[2:5], v183 offset:1264
	v_pk_fma_f32 v[46:47], v[110:111], v[36:37], v[126:127]
	v_pk_fma_f32 v[32:33], v[108:109], v[52:53], v[32:33]
	s_waitcnt lgkmcnt(9)
	v_mov_b32_e32 v180, v142
	v_mov_b32_e32 v181, v144
	v_mov_b32_e32 v144, v143
	v_pk_fma_f32 v[46:47], v[106:107], v[180:181], v[46:47]
	v_pk_fma_f32 v[32:33], v[114:115], v[144:145], v[32:33]
	s_waitcnt lgkmcnt(8)
	v_mov_b32_e32 v142, v146
	v_mov_b32_e32 v143, v148
	v_mov_b32_e32 v148, v147
	v_pk_fma_f32 v[46:47], v[94:95], v[142:143], v[46:47]
	v_pk_fma_f32 v[32:33], v[92:93], v[148:149], v[32:33]
	s_waitcnt lgkmcnt(7)
	v_mov_b32_e32 v136, v40
	v_mov_b32_e32 v137, v42
	v_mov_b32_e32 v42, v41
	v_pk_fma_f32 v[46:47], v[88:89], v[136:137], v[46:47]
	v_pk_fma_f32 v[32:33], v[86:87], v[42:43], v[32:33]
	s_waitcnt lgkmcnt(6)
	v_mov_b32_e32 v134, v26
	v_mov_b32_e32 v135, v28
	v_mov_b32_e32 v28, v27
	v_pk_fma_f32 v[40:41], v[84:85], v[134:135], v[46:47]
	v_pk_fma_f32 v[26:27], v[82:83], v[28:29], v[32:33]
	s_waitcnt lgkmcnt(5)
	v_mov_b32_e32 v132, v22
	v_mov_b32_e32 v133, v24
	v_mov_b32_e32 v24, v23
	v_pk_fma_f32 v[32:33], v[80:81], v[132:133], v[40:41]
	v_pk_fma_f32 v[22:23], v[78:79], v[24:25], v[26:27]
	s_waitcnt lgkmcnt(4)
	v_mov_b32_e32 v130, v18
	v_mov_b32_e32 v131, v20
	v_mov_b32_e32 v20, v19
	v_pk_fma_f32 v[26:27], v[72:73], v[130:131], v[32:33]
	v_pk_fma_f32 v[18:19], v[70:71], v[20:21], v[22:23]
	s_waitcnt lgkmcnt(3)
; #define LAS __attribute__((address_space(3)))
; __device__ __forceinline__ void gdn_steps(const Ctx& c, int l, int row0, int nsteps, int hh, float (&S)[64], LAS float* wl, int lane) {
;     ...
;         for (int d = 0; d < 64; d += 4) { const f32x4 k4 = *(const LAS f32x4*)(kb + d); u0 += k4[0] * S[d]; u1 += k4[1] * S[d + 1]; u2 += k4[2] * S[d + 2]; u3 += k4[3] * S[d + 3]; }
;         const float u = (u0 + u1) + (u2 + u3);
;         const float w = bv * (vv - al * u);
;         float o0 = 0.f, o1 = 0.f, o2 = 0.f, o3 = 0.f;
; #pragma unroll
;         for (int d = 0; d < 64; d += 4) { const f32x4 k4 = *(const LAS f32x4*)(kb + d); const f32x4 q4 = *(const LAS f32x4*)(qb + d);
;             S[d] = al * S[d] + k4[0] * w; S[d + 1] = al * S[d + 1] + k4[1] * w; S[d + 2] = al * S[d + 2] + k4[2] * w; S[d + 3] = al * S[d + 3] + k4[3] * w;
;             o0 += q4[0] * S[d]; o1 += q4[1] * S[d + 1]; o2 += q4[2] * S[d + 2]; o3 += q4[3] * S[d + 3]; }
	v_mov_b32_e32 v128, v14
	v_mov_b32_e32 v129, v16
	v_mov_b32_e32 v16, v15
	v_pk_fma_f32 v[22:23], v[76:77], v[128:129], v[26:27]
	v_pk_fma_f32 v[14:15], v[74:75], v[16:17], v[18:19]
	s_waitcnt lgkmcnt(2)
	v_mov_b32_e32 v126, v10
	v_mov_b32_e32 v127, v12
	v_mov_b32_e32 v12, v11
	v_pk_fma_f32 v[18:19], v[68:69], v[126:127], v[22:23]
	v_pk_fma_f32 v[10:11], v[66:67], v[12:13], v[14:15]
	s_waitcnt lgkmcnt(1)
	v_mov_b32_e32 v50, v6
	v_mov_b32_e32 v51, v8
	v_mov_b32_e32 v8, v7
	v_pk_fma_f32 v[14:15], v[64:65], v[50:51], v[18:19]
	v_pk_fma_f32 v[6:7], v[62:63], v[8:9], v[10:11]
	s_waitcnt lgkmcnt(0)
	v_mov_b32_e32 v46, v2
	v_mov_b32_e32 v47, v4
	v_mov_b32_e32 v4, v3
	v_pk_fma_f32 v[10:11], v[60:61], v[46:47], v[14:15]
	v_pk_fma_f32 v[2:3], v[56:57], v[4:5], v[6:7]
	ds_read_b128 v[150:153], v183 offset:1280
	ds_read_b128 v[154:157], v183 offset:1296
	ds_read_b128 v[158:161], v183 offset:1312
	ds_read_b128 v[162:165], v183 offset:1328
	ds_read_b128 v[166:169], v183 offset:1344
	v_pk_add_f32 v[2:3], v[10:11], v[2:3]
	s_waitcnt lgkmcnt(4)
	v_mov_b32_e32 v6, v150
	v_add_f32_e32 v2, v2, v3
	s_waitcnt vmcnt(2)
	v_fma_f32 v2, -v96, v2, v141
	v_mul_f32_e32 v182, v97, v2
	v_pk_mul_f32 v[2:3], v[170:171], v[182:183] op_sel_hi:[1,0]
	v_mov_b32_e32 v7, v152
	v_pk_fma_f32 v[2:3], v[122:123], v[96:97], v[2:3] op_sel_hi:[1,0,1]
	s_waitcnt lgkmcnt(3)
	v_mov_b32_e32 v14, v154
	v_pk_fma_f32 v[10:11], v[6:7], v[2:3], 0 op_sel_hi:[1,1,0]
	v_pk_mul_f32 v[6:7], v[172:173], v[182:183] op_sel_hi:[1,0]
	v_mov_b32_e32 v15, v156
	v_pk_fma_f32 v[6:7], v[120:121], v[96:97], v[6:7] op_sel_hi:[1,0,1]
	s_waitcnt lgkmcnt(2)
	v_mov_b32_e32 v18, v158
	v_pk_fma_f32 v[14:15], v[14:15], v[6:7], v[10:11]
	v_pk_mul_f32 v[10:11], v[174:175], v[182:183] op_sel_hi:[1,0]
	v_mov_b32_e32 v19, v160
	v_pk_fma_f32 v[10:11], v[118:119], v[96:97], v[10:11] op_sel_hi:[1,0,1]
	s_waitcnt lgkmcnt(1)
	v_mov_b32_e32 v22, v162
	v_pk_fma_f32 v[18:19], v[18:19], v[10:11], v[14:15]
	v_pk_mul_f32 v[14:15], v[176:177], v[182:183] op_sel_hi:[1,0]
	v_mov_b32_e32 v23, v164
	v_pk_fma_f32 v[14:15], v[116:117], v[96:97], v[14:15] op_sel_hi:[1,0,1]
	s_waitcnt lgkmcnt(0)
	v_mov_b32_e32 v26, v166
	v_pk_fma_f32 v[22:23], v[22:23], v[14:15], v[18:19]
	v_pk_mul_f32 v[18:19], v[178:179], v[182:183] op_sel_hi:[1,0]
	v_mov_b32_e32 v27, v168
	v_pk_fma_f32 v[18:19], v[124:125], v[96:97], v[18:19] op_sel_hi:[1,0,1]
	v_mov_b32_e32 v152, v151
	v_pk_fma_f32 v[124:125], v[26:27], v[18:19], v[22:23]
	v_pk_mul_f32 v[22:23], v[48:49], v[182:183] op_sel_hi:[1,0]
	v_pk_mul_f32 v[26:27], v[44:45], v[182:183] op_sel_hi:[1,0]
	v_pk_fma_f32 v[22:23], v[104:105], v[96:97], v[22:23] op_sel_hi:[1,0,1]
	v_pk_fma_f32 v[26:27], v[102:103], v[96:97], v[26:27] op_sel_hi:[1,0,1]
	v_pk_fma_f32 v[32:33], v[152:153], v[22:23], 0 op_sel_hi:[1,1,0]
	v_mov_b32_e32 v156, v155
	ds_read_b128 v[116:119], v183 offset:1360
	v_pk_fma_f32 v[40:41], v[156:157], v[26:27], v[32:33]
	v_pk_mul_f32 v[32:33], v[38:39], v[182:183] op_sel_hi:[1,0]
	v_mov_b32_e32 v160, v159
	v_pk_fma_f32 v[32:33], v[100:101], v[96:97], v[32:33] op_sel_hi:[1,0,1]
	v_pk_mul_f32 v[34:35], v[34:35], v[182:183] op_sel_hi:[1,0]
	v_pk_fma_f32 v[38:39], v[160:161], v[32:33], v[40:41]
	v_pk_fma_f32 v[34:35], v[98:99], v[96:97], v[34:35] op_sel_hi:[1,0,1]
	v_mov_b32_e32 v164, v163
	v_pk_mul_f32 v[30:31], v[30:31], v[182:183] op_sel_hi:[1,0]
	ds_read_b128 v[98:101], v183 offset:1376
	ds_read_b128 v[102:105], v183 offset:1392
	v_pk_fma_f32 v[38:39], v[164:165], v[34:35], v[38:39]
	v_pk_fma_f32 v[30:31], v[112:113], v[96:97], v[30:31] op_sel_hi:[1,0,1]
	v_mov_b32_e32 v168, v167
	v_pk_fma_f32 v[48:49], v[168:169], v[30:31], v[38:39]
	v_pk_mul_f32 v[36:37], v[36:37], v[182:183] op_sel_hi:[1,0]
	v_pk_mul_f32 v[38:39], v[52:53], v[182:183] op_sel_hi:[1,0]
	v_pk_fma_f32 v[36:37], v[110:111], v[96:97], v[36:37] op_sel_hi:[1,0,1]
	s_waitcnt lgkmcnt(2)
	v_mov_b32_e32 v158, v116
	v_mov_b32_e32 v159, v118
	v_pk_fma_f32 v[38:39], v[108:109], v[96:97], v[38:39] op_sel_hi:[1,0,1]
	v_mov_b32_e32 v118, v117
	v_pk_mul_f32 v[40:41], v[180:181], v[182:183] op_sel_hi:[1,0]
	v_pk_mul_f32 v[52:53], v[142:143], v[182:183] op_sel_hi:[1,0]
	v_pk_fma_f32 v[40:41], v[106:107], v[96:97], v[40:41] op_sel_hi:[1,0,1]
	v_pk_fma_f32 v[124:125], v[158:159], v[36:37], v[124:125]
	v_pk_fma_f32 v[48:49], v[118:119], v[38:39], v[48:49]
	s_waitcnt lgkmcnt(1)
	v_mov_b32_e32 v118, v98
	v_mov_b32_e32 v119, v100
	v_pk_mul_f32 v[44:45], v[144:145], v[182:183] op_sel_hi:[1,0]
	v_pk_fma_f32 v[118:119], v[118:119], v[40:41], v[124:125]
	v_mov_b32_e32 v100, v99
	v_pk_fma_f32 v[52:53], v[94:95], v[96:97], v[52:53] op_sel_hi:[1,0,1]
	s_waitcnt lgkmcnt(0)
	v_mov_b32_e32 v94, v102
	v_mov_b32_e32 v95, v104
	v_pk_mul_f32 v[98:99], v[136:137], v[182:183] op_sel_hi:[1,0]
	v_pk_mul_f32 v[42:43], v[42:43], v[182:183] op_sel_hi:[1,0]
	v_pk_fma_f32 v[44:45], v[114:115], v[96:97], v[44:45] op_sel_hi:[1,0,1]
	v_pk_mul_f32 v[160:161], v[148:149], v[182:183] op_sel_hi:[1,0]
	ds_read_b128 v[106:109], v183 offset:1408
	ds_read_b128 v[110:113], v183 offset:1424
	ds_read_b128 v[114:117], v183 offset:1440
	ds_read_b128 v[120:123], v183 offset:1456
	ds_read_b128 v[142:145], v183 offset:1472
	ds_read_b128 v[146:149], v183 offset:1488
	ds_read_b128 v[150:153], v183 offset:1504
	ds_read_b128 v[154:157], v183 offset:1520
	v_pk_fma_f32 v[94:95], v[52:53], v[94:95], v[118:119]
	v_pk_fma_f32 v[88:89], v[88:89], v[96:97], v[98:99] op_sel_hi:[1,0,1]
	v_pk_fma_f32 v[42:43], v[86:87], v[96:97], v[42:43] op_sel_hi:[1,0,1]
	s_waitcnt lgkmcnt(7)
; __device__ __forceinline__ unsigned f2bf(float f) { unsigned u = __float_as_uint(f); return (u + 0x7fffu + ((u >> 16) & 1u)) >> 16; }
; __device__ __forceinline__ float siluf_(float x) { return x / (1.0f + __expf(-x)); }
; __device__ __forceinline__ void gdn_steps(const Ctx& c, int l, int row0, int nsteps, int hh, float (&S)[64], LAS float* wl, int lane) {
;     ...
;             o0 += q4[0] * S[d]; o1 += q4[1] * S[d + 1]; o2 += q4[2] * S[d + 2]; o3 += q4[3] * S[d + 3]; }
;         const float ov = (o0 + o1) + (o2 + o3);
;         const float ms = wave_sum(ov * ov) * (1.f / 64.f);
;         MIX[(size_t)m * DM + 512 + hh * 64 + lane] = (bf16)f2bf(ov * rsqrtf(ms + RMS_EPS) * nw * siluf_(zv));
	v_mov_b32_e32 v86, v106
	v_mov_b32_e32 v87, v108
	v_pk_fma_f32 v[86:87], v[88:89], v[86:87], v[94:95]
	v_pk_mul_f32 v[94:95], v[134:135], v[182:183] op_sel_hi:[1,0]
	v_pk_mul_f32 v[28:29], v[28:29], v[182:183] op_sel_hi:[1,0]
	v_pk_fma_f32 v[84:85], v[84:85], v[96:97], v[94:95] op_sel_hi:[1,0,1]
	v_pk_fma_f32 v[28:29], v[82:83], v[96:97], v[28:29] op_sel_hi:[1,0,1]
	s_waitcnt lgkmcnt(6)
	v_mov_b32_e32 v82, v110
	v_mov_b32_e32 v83, v112
	v_pk_fma_f32 v[82:83], v[84:85], v[82:83], v[86:87]
	v_pk_mul_f32 v[86:87], v[132:133], v[182:183] op_sel_hi:[1,0]
	v_pk_mul_f32 v[24:25], v[24:25], v[182:183] op_sel_hi:[1,0]
	v_pk_fma_f32 v[48:49], v[100:101], v[44:45], v[48:49]
	v_pk_fma_f32 v[92:93], v[92:93], v[96:97], v[160:161] op_sel_hi:[1,0,1]
	v_mov_b32_e32 v104, v103
	v_pk_fma_f32 v[80:81], v[80:81], v[96:97], v[86:87] op_sel_hi:[1,0,1]
	v_pk_fma_f32 v[24:25], v[78:79], v[96:97], v[24:25] op_sel_hi:[1,0,1]
	s_waitcnt lgkmcnt(5)
	v_mov_b32_e32 v78, v114
	v_mov_b32_e32 v79, v116
	v_pk_fma_f32 v[48:49], v[92:93], v[104:105], v[48:49]
	v_mov_b32_e32 v108, v107
	v_pk_fma_f32 v[78:79], v[80:81], v[78:79], v[82:83]
	v_pk_mul_f32 v[82:83], v[130:131], v[182:183] op_sel_hi:[1,0]
	v_pk_mul_f32 v[20:21], v[20:21], v[182:183] op_sel_hi:[1,0]
	v_pk_fma_f32 v[48:49], v[42:43], v[108:109], v[48:49]
	v_mov_b32_e32 v112, v111
	v_pk_fma_f32 v[72:73], v[72:73], v[96:97], v[82:83] op_sel_hi:[1,0,1]
	v_pk_fma_f32 v[20:21], v[70:71], v[96:97], v[20:21] op_sel_hi:[1,0,1]
	s_waitcnt lgkmcnt(4)
	v_mov_b32_e32 v70, v120
	v_mov_b32_e32 v71, v122
	v_pk_fma_f32 v[48:49], v[28:29], v[112:113], v[48:49]
	v_mov_b32_e32 v116, v115
	v_pk_fma_f32 v[70:71], v[72:73], v[70:71], v[78:79]
	v_pk_mul_f32 v[78:79], v[128:129], v[182:183] op_sel_hi:[1,0]
	v_pk_mul_f32 v[16:17], v[16:17], v[182:183] op_sel_hi:[1,0]
	v_pk_fma_f32 v[48:49], v[24:25], v[116:117], v[48:49]
	v_mov_b32_e32 v122, v121
	v_pk_fma_f32 v[76:77], v[76:77], v[96:97], v[78:79] op_sel_hi:[1,0,1]
	v_pk_fma_f32 v[16:17], v[74:75], v[96:97], v[16:17] op_sel_hi:[1,0,1]
	s_waitcnt lgkmcnt(3)
	v_mov_b32_e32 v74, v142
	v_mov_b32_e32 v75, v144
	v_pk_fma_f32 v[48:49], v[20:21], v[122:123], v[48:49]
	v_pk_fma_f32 v[70:71], v[76:77], v[74:75], v[70:71]
	v_mov_b32_e32 v144, v143
	v_pk_mul_f32 v[74:75], v[126:127], v[182:183] op_sel_hi:[1,0]
	v_pk_mul_f32 v[12:13], v[12:13], v[182:183] op_sel_hi:[1,0]
	v_pk_fma_f32 v[48:49], v[16:17], v[144:145], v[48:49]
	v_pk_fma_f32 v[68:69], v[68:69], v[96:97], v[74:75] op_sel_hi:[1,0,1]
	v_pk_fma_f32 v[12:13], v[66:67], v[96:97], v[12:13] op_sel_hi:[1,0,1]
	s_waitcnt lgkmcnt(2)
	v_mov_b32_e32 v66, v146
	v_mov_b32_e32 v67, v148
	v_mov_b32_e32 v148, v147
	v_pk_mul_f32 v[50:51], v[50:51], v[182:183] op_sel_hi:[1,0]
	v_pk_mul_f32 v[8:9], v[8:9], v[182:183] op_sel_hi:[1,0]
	v_pk_fma_f32 v[66:67], v[68:69], v[66:67], v[70:71]
	v_pk_fma_f32 v[48:49], v[12:13], v[148:149], v[48:49]
	v_pk_fma_f32 v[50:51], v[64:65], v[96:97], v[50:51] op_sel_hi:[1,0,1]
	v_pk_fma_f32 v[8:9], v[62:63], v[96:97], v[8:9] op_sel_hi:[1,0,1]
	s_waitcnt lgkmcnt(1)
	v_mov_b32_e32 v62, v150
	v_mov_b32_e32 v63, v152
	v_mov_b32_e32 v152, v151
	v_pk_mul_f32 v[46:47], v[46:47], v[182:183] op_sel_hi:[1,0]
	v_pk_mul_f32 v[4:5], v[4:5], v[182:183] op_sel_hi:[1,0]
	v_pk_fma_f32 v[62:63], v[50:51], v[62:63], v[66:67]
	v_pk_fma_f32 v[48:49], v[8:9], v[152:153], v[48:49]
	v_pk_fma_f32 v[46:47], v[60:61], v[96:97], v[46:47] op_sel_hi:[1,0,1]
	v_pk_fma_f32 v[4:5], v[56:57], v[96:97], v[4:5] op_sel_hi:[1,0,1]
	s_waitcnt lgkmcnt(0)
	v_mov_b32_e32 v56, v154
	v_mov_b32_e32 v57, v156
	v_mov_b32_e32 v156, v155
	v_pk_fma_f32 v[56:57], v[46:47], v[56:57], v[62:63]
	v_pk_fma_f32 v[48:49], v[4:5], v[156:157], v[48:49]
	s_waitcnt vmcnt(0)
	v_lshlrev_b32_e32 v62, 16, v140
	v_pk_add_f32 v[48:49], v[56:57], v[48:49]
	v_mul_f32_e32 v63, 0xbfb8aa3b, v62
	v_add_f32_e32 v56, v48, v49
	v_and_b32_e32 v49, 64, v223
	v_add_u32_e32 v57, 64, v49
	v_xor_b32_e32 v49, 1, v223
	v_cmp_lt_i32_e32 vcc, v49, v57
	v_mul_f32_e32 v48, v56, v56
	v_exp_f32_e32 v63, v63
	v_cndmask_b32_e32 v49, v223, v49, vcc
	v_lshlrev_b32_e32 v49, 2, v49
	ds_bpermute_b32 v48, v49, v48
	v_xor_b32_e32 v49, 2, v223
	v_cmp_lt_i32_e32 vcc, v49, v57
	v_add_f32_e32 v63, 1.0, v63
	s_waitcnt lgkmcnt(0)
	v_fmac_f32_e32 v48, v56, v56
	v_cndmask_b32_e32 v49, v223, v49, vcc
	v_lshlrev_b32_e32 v49, 2, v49
	ds_bpermute_b32 v49, v49, v48
	s_waitcnt lgkmcnt(0)
	v_add_f32_e32 v60, v48, v49
	v_xor_b32_e32 v48, 4, v223
	v_cmp_lt_i32_e32 vcc, v48, v57
	s_nop 1
	v_cndmask_b32_e32 v48, v223, v48, vcc
	v_lshlrev_b32_e32 v48, 2, v48
	ds_bpermute_b32 v61, v48, v60
	v_lshl_add_u64 v[48:49], s[2:3], 0, v[90:91]
	v_div_scale_f32 v64, s[2:3], v63, v63, v62
	v_rcp_f32_e32 v65, v64
	s_waitcnt lgkmcnt(0)
	v_add_f32_e32 v60, v60, v61
	v_xor_b32_e32 v61, 8, v223
	v_cmp_lt_i32_e32 vcc, v61, v57
	v_fma_f32 v66, -v64, v65, 1.0
	v_fmac_f32_e32 v65, v66, v65
	v_cndmask_b32_e32 v61, v223, v61, vcc
	v_lshlrev_b32_e32 v61, 2, v61
	ds_bpermute_b32 v61, v61, v60
	s_waitcnt lgkmcnt(0)
	v_add_f32_e32 v60, v60, v61
	v_xor_b32_e32 v61, 16, v223
	v_cmp_lt_i32_e32 vcc, v61, v57
	s_nop 1
	v_cndmask_b32_e32 v61, v223, v61, vcc
	v_lshlrev_b32_e32 v61, 2, v61
	ds_bpermute_b32 v61, v61, v60
	v_div_scale_f32 v66, vcc, v62, v63, v62
	s_waitcnt lgkmcnt(0)
; __device__ __forceinline__ unsigned f2bf(float f) { unsigned u = __float_as_uint(f); return (u + 0x7fffu + ((u >> 16) & 1u)) >> 16; }
; __device__ __forceinline__ float siluf_(float x) { return x / (1.0f + __expf(-x)); }
; __device__ __forceinline__ void gdn_steps(const Ctx& c, int l, int row0, int nsteps, int hh, float (&S)[64], LAS float* wl, int lane) {
;     ...
;         const float ms = wave_sum(ov * ov) * (1.f / 64.f);
;         MIX[(size_t)m * DM + 512 + hh * 64 + lane] = (bf16)f2bf(ov * rsqrtf(ms + RMS_EPS) * nw * siluf_(zv));
; __device__ __forceinline__ void gdn_item_sample(const Ctx& c, int l, int b, int hh, LAS float* wl, int lane) {
;     ...
;     float* o = AOUT + O_GSS + (((size_t)l * DB + b) * 8 + hh) * 4096;
; #pragma unroll
;     for (int d = 0; d < 64; ++d) __builtin_nontemporal_store(S[d], o + d * 64 + lane);
	v_add_f32_e32 v60, v60, v61
	v_xor_b32_e32 v61, 32, v223
	v_cmp_lt_i32_e64 s[2:3], v61, v57
	s_nop 1
	v_cndmask_b32_e64 v57, v223, v61, s[2:3]
	v_lshlrev_b32_e32 v57, 2, v57
	ds_bpermute_b32 v57, v57, v60
	s_mov_b32 s2, 0x800000
	v_mul_f32_e32 v61, v66, v65
	v_fma_f32 v67, -v64, v61, v66
	v_fmac_f32_e32 v61, v67, v65
	s_waitcnt lgkmcnt(0)
	v_add_f32_e32 v57, v60, v57
	v_fmamk_f32 v57, v57, 0x3c800000, v221
	v_mul_f32_e32 v60, 0x4b800000, v57
	v_cmp_gt_f32_e64 s[2:3], s2, v57
	v_fma_f32 v64, -v64, v61, v66
	s_nop 0
	v_cndmask_b32_e64 v57, v57, v60, s[2:3]
	v_rsq_f32_e32 v57, v57
	v_div_fmas_f32 v60, v64, v65, v61
	v_div_fixup_f32 v60, v60, v63, v62
	v_mul_f32_e32 v61, 0x45800000, v57
	v_cndmask_b32_e64 v57, v57, v61, s[2:3]
	v_mul_f32_e32 v56, v56, v57
	v_mul_f32_e32 v0, v0, v56
	v_mul_f32_e32 v0, v60, v0
	s_mov_b32 s2, 0x20700000
	v_bfe_u32 v56, v0, 16, 1
	v_add_co_u32_e32 v48, vcc, s2, v48
	v_add3_u32 v0, v0, v56, s15
	s_nop 0
	v_addc_co_u32_e32 v49, vcc, 0, v49, vcc
	global_store_short_d16_hi v[48:49], v0, off offset:1024
	ds_read_b32 v0, v1 offset:456
	ds_read_b32 v48, v1 offset:460
	s_waitcnt lgkmcnt(1)
	v_readfirstlane_b32 s2, v0
	s_waitcnt lgkmcnt(0)
	v_readfirstlane_b32 s3, v48
	s_add_u32 s2, s2, s10
	s_addc_u32 s3, s3, s11
	v_lshl_add_u64 v[48:49], s[2:3], 0, v[54:55]
	s_mov_b64 s[2:3], 0x10600000
	v_lshl_add_u64 v[54:55], v[48:49], 0, s[2:3]
	s_mov_b32 s2, 0x10601000
	v_add_co_u32_e32 v56, vcc, s2, v48
	s_mov_b32 s2, 0x10602000
	s_nop 0
	v_addc_co_u32_e32 v57, vcc, 0, v49, vcc
	global_store_dword v[56:57], v2, off offset:-4096 nt
	global_store_dword v[54:55], v22, off offset:256 nt
	global_store_dword v[54:55], v3, off offset:512 nt
	global_store_dword v[54:55], v23, off offset:768 nt
	global_store_dword v[54:55], v6, off offset:1024 nt
	global_store_dword v[54:55], v26, off offset:1280 nt
	global_store_dword v[54:55], v7, off offset:1536 nt
	global_store_dword v[54:55], v27, off offset:1792 nt
	global_store_dword v[54:55], v10, off offset:2048 nt
	global_store_dword v[54:55], v32, off offset:2304 nt
	global_store_dword v[54:55], v11, off offset:2560 nt
	global_store_dword v[54:55], v33, off offset:2816 nt
	global_store_dword v[54:55], v14, off offset:3072 nt
	global_store_dword v[54:55], v34, off offset:3328 nt
	global_store_dword v[54:55], v15, off offset:3584 nt
	global_store_dword v[54:55], v35, off offset:3840 nt
	global_store_dword v[56:57], v18, off nt
	global_store_dword v[56:57], v30, off offset:256 nt
	global_store_dword v[56:57], v19, off offset:512 nt
	global_store_dword v[56:57], v31, off offset:768 nt
	global_store_dword v[56:57], v36, off offset:1024 nt
	global_store_dword v[56:57], v38, off offset:1280 nt
	global_store_dword v[56:57], v37, off offset:1536 nt
	global_store_dword v[56:57], v39, off offset:1792 nt
	global_store_dword v[56:57], v40, off offset:2048 nt
	global_store_dword v[56:57], v44, off offset:2304 nt
	global_store_dword v[56:57], v41, off offset:2560 nt
	global_store_dword v[56:57], v45, off offset:2816 nt
	global_store_dword v[56:57], v52, off offset:3072 nt
	global_store_dword v[56:57], v92, off offset:3328 nt
	global_store_dword v[56:57], v53, off offset:3584 nt
	global_store_dword v[56:57], v93, off offset:3840 nt
	v_add_co_u32_e32 v2, vcc, s2, v48
	s_mov_b32 s2, 0x10603000
	s_nop 0
	v_addc_co_u32_e32 v3, vcc, 0, v49, vcc
	v_add_co_u32_e32 v6, vcc, s2, v48
	s_mov_b64 s[2:3], 0
	s_nop 0
	v_addc_co_u32_e32 v7, vcc, 0, v49, vcc
	global_store_dword v[6:7], v88, off offset:-4096 nt
	global_store_dword v[2:3], v42, off offset:256 nt
	global_store_dword v[2:3], v89, off offset:512 nt
	global_store_dword v[2:3], v43, off offset:768 nt
	global_store_dword v[2:3], v84, off offset:1024 nt
	global_store_dword v[2:3], v28, off offset:1280 nt
	global_store_dword v[2:3], v85, off offset:1536 nt
	global_store_dword v[2:3], v29, off offset:1792 nt
	global_store_dword v[2:3], v80, off offset:2048 nt
	global_store_dword v[2:3], v24, off offset:2304 nt
	global_store_dword v[2:3], v81, off offset:2560 nt
	global_store_dword v[2:3], v25, off offset:2816 nt
	global_store_dword v[2:3], v72, off offset:3072 nt
	global_store_dword v[2:3], v20, off offset:3328 nt
	global_store_dword v[2:3], v73, off offset:3584 nt
	global_store_dword v[2:3], v21, off offset:3840 nt
	global_store_dword v[6:7], v76, off nt
	global_store_dword v[6:7], v16, off offset:256 nt
	global_store_dword v[6:7], v77, off offset:512 nt
	global_store_dword v[6:7], v17, off offset:768 nt
	global_store_dword v[6:7], v68, off offset:1024 nt
	global_store_dword v[6:7], v12, off offset:1280 nt
	global_store_dword v[6:7], v69, off offset:1536 nt
	global_store_dword v[6:7], v13, off offset:1792 nt
	global_store_dword v[6:7], v50, off offset:2048 nt
	global_store_dword v[6:7], v8, off offset:2304 nt
	global_store_dword v[6:7], v51, off offset:2560 nt
	global_store_dword v[6:7], v9, off offset:2816 nt
	global_store_dword v[6:7], v46, off offset:3072 nt
	global_store_dword v[6:7], v4, off offset:3328 nt
	global_store_dword v[6:7], v47, off offset:3584 nt
	global_store_dword v[6:7], v5, off offset:3840 nt
